# v112 + V LDS-DMA pieces 1-3 use the immediate offset (global and LDS side) instead of separate SGPR bases
# speedup vs baseline: 1.0060x; 1.0060x over previous
.LBB0_512:
	s_lshl_b32 s24, s74, 14
	s_add_i32 s24, s75, s24
	s_mov_b32 m0, s24
	s_add_u32 s96, s84, s22
	s_addc_u32 s97, s85, s23
	global_load_lds_dwordx4 v213, s[96:97]
	s_add_i32 m0, s24, 0x400
	s_add_u32 s4, s68, s22
	s_addc_u32 s5, s69, s23
	s_add_u32 s4, s4, 0x26840000
	s_addc_u32 s5, s5, 0
	global_load_lds_dwordx4 v215, s[96:97]
	s_lshl_b32 s24, s74, 15
	s_add_i32 s24, s77, s24
	s_mov_b32 m0, s24
	s_add_u32 s96, s4, s8
	s_addc_u32 s97, s5, s9
	global_load_lds_dwordx4 v217, s[4:5]
	s_add_i32 m0, s24, 0x380
	s_nop 0
	global_load_lds_dwordx4 v217, s[4:5] offset:128
	s_add_i32 m0, s24, 0x700
	s_nop 0
	global_load_lds_dwordx4 v217, s[4:5] offset:256
	s_add_i32 m0, s24, 0xa80
	s_nop 0
	global_load_lds_dwordx4 v217, s[4:5] offset:384

.LBB0_905:
	s_lshl_b32 s24, s78, 14
	s_add_i32 s24, s79, s24
	s_mov_b32 m0, s24
	s_add_u32 s96, s84, s22
	s_addc_u32 s97, s85, s23
	global_load_lds_dwordx4 v213, s[96:97]
	s_add_i32 m0, s24, 0x400
	s_add_u32 s4, s76, s22
	s_addc_u32 s5, s77, s23
	s_add_u32 s4, s4, 0x26840000
	s_addc_u32 s5, s5, 0
	global_load_lds_dwordx4 v215, s[96:97]
	s_lshl_b32 s24, s78, 15
	s_add_i32 s24, s81, s24
	s_mov_b32 m0, s24
	s_add_u32 s96, s4, s8
	s_addc_u32 s97, s5, s9
	global_load_lds_dwordx4 v217, s[4:5]
	s_add_i32 m0, s24, 0x380
	s_nop 0
	global_load_lds_dwordx4 v217, s[4:5] offset:128
	s_add_i32 m0, s24, 0x700
	s_nop 0
	global_load_lds_dwordx4 v217, s[4:5] offset:256
	s_add_i32 m0, s24, 0xa80
	s_nop 0
	global_load_lds_dwordx4 v217, s[4:5] offset:384
